# ph2 GEMM tail (128 tiles) run as 256 half tiles on all workgroups
# speedup vs baseline: 1.0329x; 1.0013x over previous
.LBB0_779:
	v_readlane_b32 s34, v255, 31
	v_readlane_b32 s35, v255, 32
	s_mul_i32 s34, s8, 0xd800
	s_add_u32 s50, s46, 0x5e00000
	s_mov_b32 s1, s35
	s_addc_u32 s51, s47, 0
	v_writelane_b32 v255, s0, 31
	s_lshl_b64 s[34:35], s[34:35], 2
	v_mov_b32_e32 v169, v1
	v_writelane_b32 v255, s1, 32
	s_add_u32 s1, s46, s34
	s_addc_u32 s34, s47, s35
	s_add_u32 s69, s1, 0x5d00000
	s_addc_u32 s70, s34, 0
	s_ashr_i32 s1, s31, 31
	s_lshr_b32 s1, s1, 26
	s_add_i32 s1, s31, s1
	s_ashr_i32 s78, s1, 6
	s_lshl_b32 s1, s18, 13
	s_lshl_b32 s18, s19, 12
	s_and_b32 s34, s18, 0x3000
	s_add_u32 s18, s26, 0x80
	s_addc_u32 s19, s27, 0
	s_waitcnt vmcnt(2)
	s_barrier
	s_add_i32 m0, s3, 0x18000
	v_lshl_add_u64 v[2:3], s[18:19], 0, v[168:169]
	v_mov_b32_e32 v173, v1
	global_load_lds_dwordx4 v[2:3], off
	s_add_i32 m0, s3, 0x1a000
	v_lshl_add_u64 v[2:3], s[18:19], 0, v[172:173]
	s_add_u32 s18, s36, 0x80
	v_mov_b32_e32 v167, v1
	s_addc_u32 s19, s37, 0
	s_add_i32 s72, s3, 0x8000
	v_mov_b32_e32 v171, v1
	global_load_lds_dwordx4 v[2:3], off
	s_mov_b32 m0, s72
	v_lshl_add_u64 v[2:3], s[18:19], 0, v[166:167]
	s_add_i32 s73, s3, 0xa000
	global_load_lds_dwordx4 v[2:3], off
	v_lshl_add_u64 v[2:3], s[18:19], 0, v[170:171]
	s_add_u32 s18, s26, 0x40080
	s_mov_b32 m0, s73
	s_addc_u32 s19, s27, 0
	global_load_lds_dwordx4 v[2:3], off
	s_add_i32 m0, s3, 0x1c000
	v_lshl_add_u64 v[2:3], s[18:19], 0, v[168:169]
	global_load_lds_dwordx4 v[2:3], off
	v_lshl_add_u64 v[2:3], s[18:19], 0, v[172:173]
	s_add_i32 m0, s3, 0x1e000
	s_cmp_gt_i32 s31, 63
	global_load_lds_dwordx4 v[2:3], off
	v_and_b32_e32 v2, 15, v0
	v_and_b32_e32 v3, 48, v0
	v_lshlrev_b32_e32 v2, 6, v2
	v_lshlrev_b32_e32 v0, 2, v0
	v_or_b32_e32 v4, v2, v3
	v_and_b32_e32 v0, 32, v0
	s_waitcnt vmcnt(6)
	s_cselect_b64 s[56:57], -1, 0
	s_add_i32 s71, s78, -2
	v_bitop3_b32 v2, v2, v0, v3 bitop3:0x36
	v_bitop3_b32 v0, v4, s1, v0 bitop3:0xde
	s_cmpk_lt_u32 s30, 0x100
	v_or_b32_e32 v214, s34, v2
	s_cselect_b64 s[60:61], -1, 0
	s_ashr_i32 s79, s22, 31
	s_mov_b32 s80, 0
	s_mov_b32 s100, 0
	s_mov_b32 s101, 0
	v_add_u32_e32 v215, 0, v0
	s_barrier
	s_branch .LBB0_782

.LBB0_781:
	s_mov_b32 s100, s101
	s_andn2_b64 vcc, exec, s[0:1]
	s_mov_b32 s0, s62
	s_mov_b32 s2, s54
	s_mov_b64 s[26:27], s[34:35]
	s_mov_b64 s[36:37], s[30:31]
	s_cbranch_vccz .LBB0_825
.LBB0_782:
	s_add_i32 s80, s80, 1
	s_mul_i32 s1, s80, s15
	s_mul_hi_u32 s18, s80, s64
	s_add_i32 s1, s18, s1
	s_mul_i32 s18, s80, s64
	s_add_u32 s18, s18, s22
	s_addc_u32 s19, s1, s79
	s_mov_b32 s101, 0
	s_cmp_lg_u32 s80, 2
	s_cbranch_scc1 .Lh2_a
	s_mov_b32 s19, 0
	s_and_b32 s101, s22, 1
	s_add_i32 s101, s101, 1
	s_lshr_b32 s18, s22, 1
	s_addk_i32 s18, 0x200
.Lh2_a:
	v_cmp_gt_i64_e32 vcc, s[18:19], v[188:189]
	v_cmp_lt_i64_e64 s[40:41], s[18:19], v[186:187]
	s_cbranch_vccnz .LBB0_784
	s_ashr_i32 s1, s18, 31
	s_lshr_b32 s1, s1, 29
	s_add_i32 s1, s18, s1
	s_ashr_i32 s19, s1, 3
	s_and_b32 s1, s1, -8
	s_sub_i32 s1, s18, s1
	s_cmp_lt_i32 s1, 0
	s_movk_i32 s18, 0x51
	s_cselect_b32 s18, s18, 0x50
	s_mul_i32 s1, s18, s1
	s_add_i32 s1, s1, s19
	s_ashr_i32 s18, s1, 31
	s_lshr_b32 s18, s18, 27
	s_add_i32 s18, s1, s18
	s_ashr_i32 s19, s18, 5
	s_lshl_b32 s19, s19, 2
	s_sub_i32 s30, 0x50, s19
	s_min_i32 s30, s30, 4
	s_abs_i32 s31, s30
	v_cvt_f32_u32_e32 v0, s31
	s_sub_i32 s35, 0, s31
	s_andn2_b32 s18, s18, 31
	s_sub_i32 s1, s1, s18
	v_rcp_iflag_f32_e32 v0, v0
	s_abs_i32 s18, s1
	s_xor_b32 s34, s1, s30
	s_ashr_i32 s34, s34, 31
	v_mul_f32_e32 v0, 0x4f7ffffe, v0
	v_cvt_u32_f32_e32 v0, v0
	s_nop 0
	v_readfirstlane_b32 s42, v0
	s_mul_i32 s35, s35, s42
	s_mul_hi_u32 s35, s42, s35
	s_add_i32 s42, s42, s35
	s_mul_hi_u32 s35, s18, s42
	s_mul_i32 s42, s35, s31
	s_sub_i32 s18, s18, s42
	s_add_i32 s43, s35, 1
	s_sub_i32 s42, s18, s31
	s_cmp_ge_u32 s18, s31
	s_cselect_b32 s35, s43, s35
	s_cselect_b32 s18, s42, s18
	s_add_i32 s42, s35, 1
	s_cmp_ge_u32 s18, s31
	s_cselect_b32 s18, s42, s35
	s_xor_b32 s18, s18, s34
	s_sub_i32 s62, s18, s34
	s_mul_i32 s18, s62, s30
	s_sub_i32 s1, s1, s18
	s_add_i32 s54, s1, s19
.LBB0_784:
	s_ashr_i32 s55, s54, 31
	s_lshl_b64 s[18:19], s[54:55], 19
	s_add_u32 s30, s16, s18
	s_addc_u32 s31, s17, s19
	s_cmp_lg_u32 s101, 2
	s_cbranch_scc1 .Lh2_b
	s_add_u32 s30, s30, 0x40000
	s_addc_u32 s31, s31, 0
.Lh2_b:
	s_ashr_i32 s63, s62, 31
	s_lshl_b64 s[18:19], s[62:63], 19
	s_add_u32 s34, s21, s18
	v_mov_b32_e32 v145, 0
	s_addc_u32 s35, s23, s19
	s_andn2_b64 vcc, exec, s[56:57]
	s_cbranch_vccnz .LBB0_788
	s_and_b64 s[18:19], s[40:41], exec
	s_cselect_b32 s1, s31, s37
	s_cselect_b32 s42, s30, s36
	s_cselect_b32 s43, s35, s27
	s_cselect_b32 s44, s34, s26
	s_add_u32 s45, s36, 0x100
	s_addc_u32 s55, s37, 0
	s_add_u32 s63, s26, 0x100
	v_mov_b32_e32 v2, 0
	s_addc_u32 s81, s27, 0
	s_mov_b32 s18, 0
	v_mov_b32_e32 v3, v2
	v_mov_b32_e32 v4, v2
	v_mov_b32_e32 v5, v2
	v_mov_b32_e32 v6, v2
	v_mov_b32_e32 v7, v2
	v_mov_b32_e32 v8, v2
	v_mov_b32_e32 v9, v2
	v_mov_b32_e32 v18, v2
	v_mov_b32_e32 v19, v2
	v_mov_b32_e32 v20, v2
	v_mov_b32_e32 v21, v2
	v_mov_b32_e32 v22, v2
	v_mov_b32_e32 v23, v2
	v_mov_b32_e32 v24, v2
	v_mov_b32_e32 v25, v2
	v_mov_b32_e32 v34, v2
	v_mov_b32_e32 v35, v2
	v_mov_b32_e32 v36, v2
	v_mov_b32_e32 v37, v2
	v_mov_b32_e32 v38, v2
	v_mov_b32_e32 v39, v2
	v_mov_b32_e32 v40, v2
	v_mov_b32_e32 v41, v2
	v_mov_b32_e32 v50, v2
	v_mov_b32_e32 v51, v2
	v_mov_b32_e32 v52, v2
	v_mov_b32_e32 v53, v2
	v_mov_b32_e32 v54, v2
	v_mov_b32_e32 v55, v2
	v_mov_b32_e32 v56, v2
	v_mov_b32_e32 v57, v2
	v_mov_b32_e32 v10, v2
	v_mov_b32_e32 v11, v2
	v_mov_b32_e32 v12, v2
	v_mov_b32_e32 v13, v2
	v_mov_b32_e32 v14, v2
	v_mov_b32_e32 v15, v2
	v_mov_b32_e32 v16, v2
	v_mov_b32_e32 v17, v2
	v_mov_b32_e32 v26, v2
	v_mov_b32_e32 v27, v2
	v_mov_b32_e32 v28, v2
	v_mov_b32_e32 v29, v2
	v_mov_b32_e32 v30, v2
	v_mov_b32_e32 v31, v2
	v_mov_b32_e32 v32, v2
	v_mov_b32_e32 v33, v2
	v_mov_b32_e32 v42, v2
	v_mov_b32_e32 v43, v2
	v_mov_b32_e32 v44, v2
	v_mov_b32_e32 v45, v2
	v_mov_b32_e32 v46, v2
	v_mov_b32_e32 v47, v2
	v_mov_b32_e32 v48, v2
	v_mov_b32_e32 v49, v2
	v_mov_b32_e32 v62, v2
	v_mov_b32_e32 v63, v2
	v_mov_b32_e32 v64, v2
	v_mov_b32_e32 v65, v2
	v_mov_b32_e32 v70, v2
	v_mov_b32_e32 v71, v2
	v_mov_b32_e32 v72, v2
	v_mov_b32_e32 v73, v2
	v_mov_b32_e32 v82, v2
	v_mov_b32_e32 v83, v2
	v_mov_b32_e32 v84, v2
	v_mov_b32_e32 v85, v2
	v_mov_b32_e32 v86, v2
	v_mov_b32_e32 v87, v2
	v_mov_b32_e32 v88, v2
	v_mov_b32_e32 v89, v2
	v_mov_b32_e32 v98, v2
	v_mov_b32_e32 v99, v2
	v_mov_b32_e32 v100, v2
	v_mov_b32_e32 v101, v2
	v_mov_b32_e32 v102, v2
	v_mov_b32_e32 v103, v2
	v_mov_b32_e32 v104, v2
	v_mov_b32_e32 v105, v2
	v_mov_b32_e32 v114, v2
	v_mov_b32_e32 v115, v2
	v_mov_b32_e32 v116, v2
	v_mov_b32_e32 v117, v2
	v_mov_b32_e32 v118, v2
	v_mov_b32_e32 v119, v2
	v_mov_b32_e32 v120, v2
	v_mov_b32_e32 v121, v2
	v_mov_b32_e32 v130, v2
	v_mov_b32_e32 v131, v2
	v_mov_b32_e32 v132, v2
	v_mov_b32_e32 v133, v2
	v_mov_b32_e32 v134, v2
	v_mov_b32_e32 v135, v2
	v_mov_b32_e32 v136, v2
	v_mov_b32_e32 v137, v2
	v_mov_b32_e32 v90, v2
	v_mov_b32_e32 v91, v2
	v_mov_b32_e32 v92, v2
	v_mov_b32_e32 v93, v2
	v_mov_b32_e32 v94, v2
	v_mov_b32_e32 v95, v2
	v_mov_b32_e32 v96, v2
	v_mov_b32_e32 v97, v2
	v_mov_b32_e32 v106, v2
	v_mov_b32_e32 v107, v2
	v_mov_b32_e32 v108, v2
	v_mov_b32_e32 v109, v2
	v_mov_b32_e32 v110, v2
	v_mov_b32_e32 v111, v2
	v_mov_b32_e32 v112, v2
	v_mov_b32_e32 v113, v2
	v_mov_b32_e32 v122, v2
	v_mov_b32_e32 v123, v2
	v_mov_b32_e32 v124, v2
	v_mov_b32_e32 v125, v2
	v_mov_b32_e32 v126, v2
	v_mov_b32_e32 v127, v2
	v_mov_b32_e32 v128, v2
	v_mov_b32_e32 v129, v2
	v_mov_b32_e32 v138, v2
	v_mov_b32_e32 v139, v2
	v_mov_b32_e32 v140, v2
	v_mov_b32_e32 v141, v2
	v_mov_b32_e32 v142, v2
	v_mov_b32_e32 v143, v2
	v_mov_b32_e32 v144, v2
	v_mov_b32_e32 v145, v2
.LBB0_786:
	s_add_i32 s82, s18, 2
	s_cmp_eq_u32 s71, s18
	s_cselect_b32 s18, s42, s45
	s_cselect_b32 s19, s1, s55
	s_cselect_b32 s36, s44, s63
	s_cselect_b32 s37, s43, s81
	s_add_u32 s26, s18, 0x80
	s_addc_u32 s27, s19, 0
	s_add_i32 s83, 0, 0x10000
	v_add_u32_e32 v0, s83, v214
	s_add_i32 s86, 0, 0x14000
	ds_read_b128 v[58:61], v0
	ds_read_b128 v[66:69], v0 offset:1024
	ds_read_b128 v[74:77], v0 offset:2048
	ds_read_b128 v[78:81], v0 offset:3072
	v_add_u32_e32 v0, s86, v214
	ds_read_b128 v[146:149], v0
	ds_read_b128 v[150:153], v0 offset:1024
	ds_read_b128 v[154:157], v0 offset:2048
	ds_read_b128 v[158:161], v0 offset:3072
	s_add_u32 s84, s45, 0x3ff80
	s_addc_u32 s85, s55, 0
	ds_read_b128 v[162:165], v215
	ds_read_b128 v[194:197], v215 offset:1024
	ds_read_b128 v[198:201], v215 offset:2048
	ds_read_b128 v[202:205], v215 offset:3072
	ds_read_b128 v[206:209], v215 offset:4096
	ds_read_b128 v[210:213], v215 offset:5120
	ds_read_b128 v[216:219], v215 offset:6144
	ds_read_b128 v[220:223], v215 offset:7168
	s_add_i32 m0, s3, 0xc000
	v_lshl_add_u64 v[224:225], s[84:85], 0, v[166:167]
	global_load_lds_dwordx4 v[224:225], off
	v_lshl_add_u64 v[224:225], s[84:85], 0, v[170:171]
	s_add_i32 m0, s3, 0xe000
	s_nop 0
	global_load_lds_dwordx4 v[224:225], off
	s_waitcnt vmcnt(8)
	s_waitcnt lgkmcnt(0)
	s_barrier
	s_setprio 1
	s_waitcnt lgkmcnt(0)
	v_mfma_f32_16x16x32_bf16 v[142:145], v[58:61], v[162:165], v[142:145]
	v_mfma_f32_16x16x32_bf16 v[138:141], v[74:77], v[162:165], v[138:141]
	v_mfma_f32_16x16x32_bf16 v[126:129], v[58:61], v[198:201], v[126:129]
	v_mfma_f32_16x16x32_bf16 v[122:125], v[74:77], v[198:201], v[122:125]
	v_mfma_f32_16x16x32_bf16 v[110:113], v[58:61], v[206:209], v[110:113]
	v_mfma_f32_16x16x32_bf16 v[106:109], v[74:77], v[206:209], v[106:109]
	v_mfma_f32_16x16x32_bf16 v[94:97], v[58:61], v[216:219], v[94:97]
	v_mfma_f32_16x16x32_bf16 v[90:93], v[74:77], v[216:219], v[90:93]
	v_mfma_f32_16x16x32_bf16 v[142:145], v[66:69], v[194:197], v[142:145]
	v_mfma_f32_16x16x32_bf16 v[138:141], v[78:81], v[194:197], v[138:141]
	v_mfma_f32_16x16x32_bf16 v[126:129], v[66:69], v[202:205], v[126:129]
	v_mfma_f32_16x16x32_bf16 v[122:125], v[78:81], v[202:205], v[122:125]
	v_mfma_f32_16x16x32_bf16 v[110:113], v[66:69], v[210:213], v[110:113]
	v_mfma_f32_16x16x32_bf16 v[106:109], v[78:81], v[210:213], v[106:109]
	v_mfma_f32_16x16x32_bf16 v[94:97], v[66:69], v[220:223], v[94:97]
	v_mfma_f32_16x16x32_bf16 v[90:93], v[78:81], v[220:223], v[90:93]
	v_mfma_f32_16x16x32_bf16 v[134:137], v[146:149], v[162:165], v[134:137]
	v_mfma_f32_16x16x32_bf16 v[130:133], v[154:157], v[162:165], v[130:133]
	v_mfma_f32_16x16x32_bf16 v[118:121], v[146:149], v[198:201], v[118:121]
	v_mfma_f32_16x16x32_bf16 v[114:117], v[154:157], v[198:201], v[114:117]
	v_mfma_f32_16x16x32_bf16 v[102:105], v[146:149], v[206:209], v[102:105]
	v_mfma_f32_16x16x32_bf16 v[98:101], v[154:157], v[206:209], v[98:101]
	v_mfma_f32_16x16x32_bf16 v[86:89], v[146:149], v[216:219], v[86:89]
	v_mfma_f32_16x16x32_bf16 v[82:85], v[154:157], v[216:219], v[82:85]
	v_mfma_f32_16x16x32_bf16 v[134:137], v[150:153], v[194:197], v[134:137]
	v_mfma_f32_16x16x32_bf16 v[130:133], v[158:161], v[194:197], v[130:133]
	v_mfma_f32_16x16x32_bf16 v[118:121], v[150:153], v[202:205], v[118:121]
	v_mfma_f32_16x16x32_bf16 v[114:117], v[158:161], v[202:205], v[114:117]
	v_mfma_f32_16x16x32_bf16 v[102:105], v[150:153], v[210:213], v[102:105]
	v_mfma_f32_16x16x32_bf16 v[98:101], v[158:161], v[210:213], v[98:101]
	v_mfma_f32_16x16x32_bf16 v[86:89], v[150:153], v[220:223], v[86:89]
	v_mfma_f32_16x16x32_bf16 v[82:85], v[158:161], v[220:223], v[82:85]
	s_setprio 0
	s_barrier
	s_mov_b64 s[84:85], s[36:37]
	s_add_i32 s83, s83, s25
	ds_read_b128 v[162:165], v215 offset:16384
	ds_read_b128 v[194:197], v215 offset:17408
	ds_read_b128 v[198:201], v215 offset:18432
	ds_read_b128 v[202:205], v215 offset:19456
	ds_read_b128 v[206:209], v215 offset:20480
	ds_read_b128 v[210:213], v215 offset:21504
	ds_read_b128 v[216:219], v215 offset:22528
	ds_read_b128 v[220:223], v215 offset:23552
	s_mov_b32 m0, s83
	v_lshl_add_u64 v[224:225], s[84:85], 0, v[168:169]
	global_load_lds_dwordx4 v[224:225], off
	s_add_i32 m0, s83, 0x2000
	v_lshl_add_u64 v[224:225], s[84:85], 0, v[172:173]
	s_add_u32 s84, s36, 0x40000
	s_addc_u32 s85, s37, 0
	s_add_i32 s83, s86, s25
	global_load_lds_dwordx4 v[224:225], off
	s_mov_b32 m0, s83
	v_lshl_add_u64 v[224:225], s[84:85], 0, v[168:169]
	global_load_lds_dwordx4 v[224:225], off
	v_lshl_add_u64 v[224:225], s[84:85], 0, v[172:173]
	s_add_i32 m0, s83, 0x2000
	s_mov_b64 s[84:85], s[18:19]
	global_load_lds_dwordx4 v[224:225], off
	s_mov_b32 m0, s3
	v_lshl_add_u64 v[224:225], s[84:85], 0, v[166:167]
	global_load_lds_dwordx4 v[224:225], off
	v_lshl_add_u64 v[224:225], s[84:85], 0, v[170:171]
	s_mov_b32 m0, s39
	s_nop 0
	global_load_lds_dwordx4 v[224:225], off
	s_waitcnt vmcnt(8)
	s_waitcnt lgkmcnt(0)
	s_barrier
	s_setprio 1
	s_waitcnt lgkmcnt(0)
	s_cmp_lg_u32 s100, 0
	s_cbranch_scc1 .Lh2_m0
	v_mfma_f32_16x16x32_bf16 v[70:73], v[58:61], v[162:165], v[70:73]
	v_mfma_f32_16x16x32_bf16 v[62:65], v[74:77], v[162:165], v[62:65]
	v_mfma_f32_16x16x32_bf16 v[46:49], v[58:61], v[198:201], v[46:49]
	v_mfma_f32_16x16x32_bf16 v[42:45], v[74:77], v[198:201], v[42:45]
	v_mfma_f32_16x16x32_bf16 v[30:33], v[58:61], v[206:209], v[30:33]
	v_mfma_f32_16x16x32_bf16 v[26:29], v[74:77], v[206:209], v[26:29]
	v_mfma_f32_16x16x32_bf16 v[14:17], v[58:61], v[216:219], v[14:17]
	v_mfma_f32_16x16x32_bf16 v[10:13], v[74:77], v[216:219], v[10:13]
	v_mfma_f32_16x16x32_bf16 v[70:73], v[66:69], v[194:197], v[70:73]
	v_mfma_f32_16x16x32_bf16 v[62:65], v[78:81], v[194:197], v[62:65]
	v_mfma_f32_16x16x32_bf16 v[46:49], v[66:69], v[202:205], v[46:49]
	v_mfma_f32_16x16x32_bf16 v[42:45], v[78:81], v[202:205], v[42:45]
	v_mfma_f32_16x16x32_bf16 v[30:33], v[66:69], v[210:213], v[30:33]
	v_mfma_f32_16x16x32_bf16 v[26:29], v[78:81], v[210:213], v[26:29]
	v_mfma_f32_16x16x32_bf16 v[14:17], v[66:69], v[220:223], v[14:17]
	v_mfma_f32_16x16x32_bf16 v[10:13], v[78:81], v[220:223], v[10:13]
	v_mfma_f32_16x16x32_bf16 v[54:57], v[146:149], v[162:165], v[54:57]
	v_mfma_f32_16x16x32_bf16 v[50:53], v[154:157], v[162:165], v[50:53]
	v_mfma_f32_16x16x32_bf16 v[38:41], v[146:149], v[198:201], v[38:41]
	v_mfma_f32_16x16x32_bf16 v[34:37], v[154:157], v[198:201], v[34:37]
	v_mfma_f32_16x16x32_bf16 v[22:25], v[146:149], v[206:209], v[22:25]
	v_mfma_f32_16x16x32_bf16 v[18:21], v[154:157], v[206:209], v[18:21]
	v_mfma_f32_16x16x32_bf16 v[6:9], v[146:149], v[216:219], v[6:9]
	v_mfma_f32_16x16x32_bf16 v[2:5], v[154:157], v[216:219], v[2:5]
	v_mfma_f32_16x16x32_bf16 v[54:57], v[150:153], v[194:197], v[54:57]
	v_mfma_f32_16x16x32_bf16 v[50:53], v[158:161], v[194:197], v[50:53]
	v_mfma_f32_16x16x32_bf16 v[38:41], v[150:153], v[202:205], v[38:41]
	v_mfma_f32_16x16x32_bf16 v[34:37], v[158:161], v[202:205], v[34:37]
	v_mfma_f32_16x16x32_bf16 v[22:25], v[150:153], v[210:213], v[22:25]
	v_mfma_f32_16x16x32_bf16 v[18:21], v[158:161], v[210:213], v[18:21]
	v_mfma_f32_16x16x32_bf16 v[6:9], v[150:153], v[220:223], v[6:9]
	v_mfma_f32_16x16x32_bf16 v[2:5], v[158:161], v[220:223], v[2:5]
.Lh2_m0:
	s_setprio 0
	s_barrier
	s_add_i32 s83, 0, 0x18000
	v_add_u32_e32 v0, s83, v214
	s_add_i32 s84, 0, 0x1c000
	ds_read_b128 v[58:61], v0
	ds_read_b128 v[66:69], v0 offset:1024
	ds_read_b128 v[74:77], v0 offset:2048
	ds_read_b128 v[78:81], v0 offset:3072
	v_add_u32_e32 v0, s84, v214
	ds_read_b128 v[146:149], v0
	ds_read_b128 v[150:153], v0 offset:1024
	ds_read_b128 v[154:157], v0 offset:2048
	ds_read_b128 v[158:161], v0 offset:3072
	s_add_u32 s18, s18, 0x40000
	s_addc_u32 s19, s19, 0
	s_mov_b32 m0, s67
	ds_read_b128 v[162:165], v215 offset:32768
	ds_read_b128 v[194:197], v215 offset:33792
	ds_read_b128 v[198:201], v215 offset:34816
	ds_read_b128 v[202:205], v215 offset:35840
	ds_read_b128 v[206:209], v215 offset:36864
	ds_read_b128 v[210:213], v215 offset:37888
	ds_read_b128 v[216:219], v215 offset:38912
	ds_read_b128 v[220:223], v215 offset:39936
	s_nop 0
	v_lshl_add_u64 v[224:225], s[18:19], 0, v[166:167]
	global_load_lds_dwordx4 v[224:225], off
	v_lshl_add_u64 v[224:225], s[18:19], 0, v[170:171]
	s_mov_b32 m0, s68
	s_nop 0
	global_load_lds_dwordx4 v[224:225], off
	s_waitcnt vmcnt(8)
	s_waitcnt lgkmcnt(0)
	s_barrier
	s_setprio 1
	s_waitcnt lgkmcnt(0)
	v_mfma_f32_16x16x32_bf16 v[142:145], v[58:61], v[162:165], v[142:145]
	v_mfma_f32_16x16x32_bf16 v[138:141], v[74:77], v[162:165], v[138:141]
	v_mfma_f32_16x16x32_bf16 v[126:129], v[58:61], v[198:201], v[126:129]
	v_mfma_f32_16x16x32_bf16 v[122:125], v[74:77], v[198:201], v[122:125]
	v_mfma_f32_16x16x32_bf16 v[110:113], v[58:61], v[206:209], v[110:113]
	v_mfma_f32_16x16x32_bf16 v[106:109], v[74:77], v[206:209], v[106:109]
	v_mfma_f32_16x16x32_bf16 v[94:97], v[58:61], v[216:219], v[94:97]
	v_mfma_f32_16x16x32_bf16 v[90:93], v[74:77], v[216:219], v[90:93]
	v_mfma_f32_16x16x32_bf16 v[142:145], v[66:69], v[194:197], v[142:145]
	v_mfma_f32_16x16x32_bf16 v[138:141], v[78:81], v[194:197], v[138:141]
	v_mfma_f32_16x16x32_bf16 v[126:129], v[66:69], v[202:205], v[126:129]
	v_mfma_f32_16x16x32_bf16 v[122:125], v[78:81], v[202:205], v[122:125]
	v_mfma_f32_16x16x32_bf16 v[110:113], v[66:69], v[210:213], v[110:113]
	v_mfma_f32_16x16x32_bf16 v[106:109], v[78:81], v[210:213], v[106:109]
	v_mfma_f32_16x16x32_bf16 v[94:97], v[66:69], v[220:223], v[94:97]
	v_mfma_f32_16x16x32_bf16 v[90:93], v[78:81], v[220:223], v[90:93]
	v_mfma_f32_16x16x32_bf16 v[134:137], v[146:149], v[162:165], v[134:137]
	v_mfma_f32_16x16x32_bf16 v[130:133], v[154:157], v[162:165], v[130:133]
	v_mfma_f32_16x16x32_bf16 v[118:121], v[146:149], v[198:201], v[118:121]
	v_mfma_f32_16x16x32_bf16 v[114:117], v[154:157], v[198:201], v[114:117]
	v_mfma_f32_16x16x32_bf16 v[102:105], v[146:149], v[206:209], v[102:105]
	v_mfma_f32_16x16x32_bf16 v[98:101], v[154:157], v[206:209], v[98:101]
	v_mfma_f32_16x16x32_bf16 v[86:89], v[146:149], v[216:219], v[86:89]
	v_mfma_f32_16x16x32_bf16 v[82:85], v[154:157], v[216:219], v[82:85]
	v_mfma_f32_16x16x32_bf16 v[134:137], v[150:153], v[194:197], v[134:137]
	v_mfma_f32_16x16x32_bf16 v[130:133], v[158:161], v[194:197], v[130:133]
	v_mfma_f32_16x16x32_bf16 v[118:121], v[150:153], v[202:205], v[118:121]
	v_mfma_f32_16x16x32_bf16 v[114:117], v[158:161], v[202:205], v[114:117]
	v_mfma_f32_16x16x32_bf16 v[102:105], v[150:153], v[210:213], v[102:105]
	v_mfma_f32_16x16x32_bf16 v[98:101], v[158:161], v[210:213], v[98:101]
	v_mfma_f32_16x16x32_bf16 v[86:89], v[150:153], v[220:223], v[86:89]
	v_mfma_f32_16x16x32_bf16 v[82:85], v[158:161], v[220:223], v[82:85]
	s_setprio 0
	s_barrier
	s_add_u32 s18, s36, 0x80
	s_addc_u32 s19, s37, 0
	s_add_i32 s83, s83, s25
	ds_read_b128 v[162:165], v215 offset:49152
	ds_read_b128 v[194:197], v215 offset:50176
	ds_read_b128 v[198:201], v215 offset:51200
	ds_read_b128 v[202:205], v215 offset:52224
	ds_read_b128 v[206:209], v215 offset:53248
	ds_read_b128 v[210:213], v215 offset:54272
	ds_read_b128 v[216:219], v215 offset:55296
	ds_read_b128 v[220:223], v215 offset:56320
	s_mov_b32 m0, s83
	v_lshl_add_u64 v[224:225], s[18:19], 0, v[168:169]
	global_load_lds_dwordx4 v[224:225], off
	s_add_i32 m0, s83, 0x2000
	v_lshl_add_u64 v[224:225], s[18:19], 0, v[172:173]
	s_add_u32 s18, s36, 0x40080
	s_addc_u32 s19, s37, 0
	s_add_i32 s36, s84, s25
	global_load_lds_dwordx4 v[224:225], off
	s_mov_b32 m0, s36
	v_lshl_add_u64 v[224:225], s[18:19], 0, v[168:169]
	global_load_lds_dwordx4 v[224:225], off
	v_lshl_add_u64 v[224:225], s[18:19], 0, v[172:173]
	s_add_i32 m0, s36, 0x2000
	s_nop 0
	global_load_lds_dwordx4 v[224:225], off
	s_mov_b32 m0, s72
	v_lshl_add_u64 v[224:225], s[26:27], 0, v[166:167]
	global_load_lds_dwordx4 v[224:225], off
	v_lshl_add_u64 v[224:225], s[26:27], 0, v[170:171]
	s_mov_b32 m0, s73
	s_nop 0
	global_load_lds_dwordx4 v[224:225], off
	s_waitcnt vmcnt(8)
	s_waitcnt lgkmcnt(0)
	s_barrier
	s_setprio 1
	s_waitcnt lgkmcnt(0)
	s_cmp_lg_u32 s100, 0
	s_cbranch_scc1 .Lh2_m1
	v_mfma_f32_16x16x32_bf16 v[70:73], v[58:61], v[162:165], v[70:73]
	v_mfma_f32_16x16x32_bf16 v[62:65], v[74:77], v[162:165], v[62:65]
	v_mfma_f32_16x16x32_bf16 v[46:49], v[58:61], v[198:201], v[46:49]
	v_mfma_f32_16x16x32_bf16 v[42:45], v[74:77], v[198:201], v[42:45]
	v_mfma_f32_16x16x32_bf16 v[30:33], v[58:61], v[206:209], v[30:33]
	v_mfma_f32_16x16x32_bf16 v[26:29], v[74:77], v[206:209], v[26:29]
	v_mfma_f32_16x16x32_bf16 v[14:17], v[58:61], v[216:219], v[14:17]
	v_mfma_f32_16x16x32_bf16 v[10:13], v[74:77], v[216:219], v[10:13]
	v_mfma_f32_16x16x32_bf16 v[70:73], v[66:69], v[194:197], v[70:73]
	v_mfma_f32_16x16x32_bf16 v[62:65], v[78:81], v[194:197], v[62:65]
	v_mfma_f32_16x16x32_bf16 v[46:49], v[66:69], v[202:205], v[46:49]
	v_mfma_f32_16x16x32_bf16 v[42:45], v[78:81], v[202:205], v[42:45]
	v_mfma_f32_16x16x32_bf16 v[30:33], v[66:69], v[210:213], v[30:33]
	v_mfma_f32_16x16x32_bf16 v[26:29], v[78:81], v[210:213], v[26:29]
	v_mfma_f32_16x16x32_bf16 v[14:17], v[66:69], v[220:223], v[14:17]
	v_mfma_f32_16x16x32_bf16 v[10:13], v[78:81], v[220:223], v[10:13]
	v_mfma_f32_16x16x32_bf16 v[54:57], v[146:149], v[162:165], v[54:57]
	v_mfma_f32_16x16x32_bf16 v[50:53], v[154:157], v[162:165], v[50:53]
	v_mfma_f32_16x16x32_bf16 v[38:41], v[146:149], v[198:201], v[38:41]
	v_mfma_f32_16x16x32_bf16 v[34:37], v[154:157], v[198:201], v[34:37]
	v_mfma_f32_16x16x32_bf16 v[22:25], v[146:149], v[206:209], v[22:25]
	v_mfma_f32_16x16x32_bf16 v[18:21], v[154:157], v[206:209], v[18:21]
	v_mfma_f32_16x16x32_bf16 v[6:9], v[146:149], v[216:219], v[6:9]
	v_mfma_f32_16x16x32_bf16 v[2:5], v[154:157], v[216:219], v[2:5]
	v_mfma_f32_16x16x32_bf16 v[54:57], v[150:153], v[194:197], v[54:57]
	v_mfma_f32_16x16x32_bf16 v[50:53], v[158:161], v[194:197], v[50:53]
	v_mfma_f32_16x16x32_bf16 v[38:41], v[150:153], v[202:205], v[38:41]
	v_mfma_f32_16x16x32_bf16 v[34:37], v[158:161], v[202:205], v[34:37]
	v_mfma_f32_16x16x32_bf16 v[22:25], v[150:153], v[210:213], v[22:25]
	v_mfma_f32_16x16x32_bf16 v[18:21], v[158:161], v[210:213], v[18:21]
	v_mfma_f32_16x16x32_bf16 v[6:9], v[150:153], v[220:223], v[6:9]
	v_mfma_f32_16x16x32_bf16 v[2:5], v[158:161], v[220:223], v[2:5]
.Lh2_m1:
	s_setprio 0
	s_barrier
	s_add_u32 s45, s45, 0x100
	s_addc_u32 s55, s55, 0
	s_add_u32 s63, s63, 0x100
	s_addc_u32 s81, s81, 0
	s_cmp_ge_i32 s82, s78
	s_mov_b32 s18, s82
	s_cbranch_scc0 .LBB0_786
	s_mov_b32 s81, 0xc000
	s_mov_b32 s82, 0xe000
	s_mov_b32 s83, 0xb000
	s_mov_b32 s84, 0x4ffff
	s_mov_b32 s85, 0x66666667
	s_mov_b32 s86, 0x1f000

.LBB0_790:
	s_cmp_eq_u32 s100, 2
	s_cselect_b32 vcc_lo, 0x80, 0
	s_lshl_b32 s36, s0, 8
	s_cmp_gt_i32 s0, 3
	s_cselect_b64 s[26:27], -1, 0
	s_add_i32 s1, s2, -16
	s_lshr_b32 s1, s1, 3
	v_mov_b32_e32 v0, v179
	s_add_i32 s1, s1, 1
	s_cmp_gt_i32 s2, 15
	v_ashrrev_i32_e32 v58, 2, v0
	v_and_b32_e32 v58, 0xffffffc0, v58
	s_cselect_b32 s1, s1, 0
	v_lshl_add_u32 v146, s2, 8, v58
	v_add_u32_e32 v146, vcc_lo, v146
	s_mul_hi_u32 s2, s1, 0x6000
	s_mulk_i32 s1, 0x6000
	s_add_u32 s1, s69, s1
	s_addc_u32 s2, s70, s2
	s_ashr_i32 s37, s36, 31
	v_and_b32_e32 v210, 15, v0
	v_bfe_u32 v213, v0, 4, 2
	s_lshl_b64 s[18:19], s[36:37], 2
	v_lshrrev_b32_e32 v0, 1, v0
	s_add_u32 s18, s1, s18
	v_and_b32_e32 v216, 0x60, v0
	s_addc_u32 s19, s2, s19
	v_lshlrev_b32_e32 v0, 2, v216
	v_or_b32_e32 v208, v146, v210
	v_lshl_add_u64 v[58:59], s[18:19], 0, v[0:1]
	v_lshlrev_b32_e32 v0, 5, v213
	v_add_u32_e32 v198, 0x90, v208
	v_lshl_add_u64 v[66:67], v[58:59], 0, v[0:1]
	v_lshlrev_b32_e32 v0, 4, v213
	v_ashrrev_i32_e32 v209, 31, v208
	v_ashrrev_i32_e32 v199, 31, v198
	v_lshl_add_u64 v[158:159], s[50:51], 0, v[0:1]
	v_lshlrev_b64 v[146:147], 6, v[208:209]
	v_or_b32_e32 v206, 16, v208
	v_lshlrev_b64 v[150:151], 6, v[198:199]
	v_lshl_add_u64 v[146:147], v[158:159], 0, v[146:147]
	v_ashrrev_i32_e32 v207, 31, v206
	v_lshl_add_u64 v[150:151], v[158:159], 0, v[150:151]
	global_load_dwordx4 v[74:77], v[66:67], off offset:16
	global_load_dwordx4 v[78:81], v[66:67], off
	global_load_dwordx4 v[58:61], v[66:67], off offset:528
	s_nop 0
	global_load_dwordx4 v[66:69], v[66:67], off offset:512
	v_add_u32_e32 v196, 0xa0, v208
	global_load_dwordx4 v[218:221], v[146:147], off
	global_load_dwordx4 v[154:157], v[150:151], off
	v_lshlrev_b64 v[146:147], 6, v[206:207]
	v_lshl_add_u64 v[146:147], v[158:159], 0, v[146:147]
	global_load_dwordx4 v[222:225], v[146:147], off
	v_ashrrev_i32_e32 v197, 31, v196
	v_or_b32_e32 v204, 32, v208
	v_lshlrev_b64 v[150:151], 6, v[196:197]
	v_ashrrev_i32_e32 v205, 31, v204
	v_lshl_add_u64 v[150:151], v[158:159], 0, v[150:151]
	v_or_b32_e32 v202, 48, v208
	global_load_dwordx4 v[150:153], v[150:151], off
	v_lshlrev_b64 v[146:147], 6, v[204:205]
	v_lshl_add_u64 v[146:147], v[158:159], 0, v[146:147]
	v_ashrrev_i32_e32 v203, 31, v202
	global_load_dwordx4 v[226:229], v[146:147], off
	v_lshlrev_b64 v[146:147], 6, v[202:203]
	v_lshl_add_u64 v[146:147], v[158:159], 0, v[146:147]
	v_add_u32_e32 v200, 0x80, v208
	global_load_dwordx4 v[162:165], v[146:147], off
	v_ashrrev_i32_e32 v201, 31, v200
	v_lshlrev_b64 v[146:147], 6, v[200:201]
	v_lshl_add_u64 v[146:147], v[158:159], 0, v[146:147]
	global_load_dwordx4 v[146:149], v[146:147], off
	v_add_u32_e32 v194, 0xb0, v208
	v_ashrrev_i32_e32 v195, 31, v194
	v_lshlrev_b64 v[160:161], 6, v[194:195]
	v_lshl_add_u64 v[158:159], v[158:159], 0, v[160:161]
	global_load_dwordx4 v[158:161], v[158:159], off
	v_lshlrev_b32_e32 v0, 6, v213
	v_lshlrev_b32_e32 v210, 2, v210
	v_bitop3_b32 v217, v0, 64, v210 bitop3:0x36
	v_bitop3_b32 v0, v0, s90, v210 bitop3:0x36
	s_cmp_lt_i32 s0, 4
	s_waitcnt vmcnt(0)
	v_mov_b32_e32 v210, v219
	v_mov_b32_e32 v211, v220
	v_mov_b32_e32 v219, v221
	v_pk_add_f32 v[210:211], v[210:211], v[218:219]
	v_mov_b32_e32 v218, v223
	v_mov_b32_e32 v219, v224
	v_mov_b32_e32 v223, v225
	v_pk_add_f32 v[218:219], v[218:219], v[222:223]
	v_mov_b32_e32 v221, v210
	v_mov_b32_e32 v220, v218
	v_mov_b32_e32 v210, v219
	v_pk_add_f32 v[210:211], v[220:221], v[210:211]
	ds_bpermute_b32 v219, v217, v211
	ds_bpermute_b32 v218, v217, v210
	s_waitcnt lgkmcnt(0)
	v_pk_add_f32 v[210:211], v[210:211], v[218:219]
	ds_bpermute_b32 v219, v0, v211
	ds_bpermute_b32 v218, v0, v210
	v_mov_b32_e32 v220, v163
	v_mov_b32_e32 v221, v164
	v_mov_b32_e32 v163, v165
	v_pk_add_f32 v[162:163], v[220:221], v[162:163]
	s_waitcnt lgkmcnt(0)
	v_pk_add_f32 v[210:211], v[210:211], v[218:219]
	v_mov_b32_e32 v218, v227
	v_mov_b32_e32 v219, v228
	v_mov_b32_e32 v227, v229
	v_pk_add_f32 v[218:219], v[218:219], v[226:227]
	v_mov_b32_e32 v164, v162
	v_mov_b32_e32 v165, v218
	v_mov_b32_e32 v218, v163
	v_pk_add_f32 v[162:163], v[164:165], v[218:219]
	v_mov_b32_e32 v218, v147
	v_mov_b32_e32 v219, v148
	v_mov_b32_e32 v147, v149
	v_mov_b32_e32 v148, v155
	v_mov_b32_e32 v149, v156
	v_mov_b32_e32 v155, v157
	v_pk_add_f32 v[146:147], v[218:219], v[146:147]
	v_pk_add_f32 v[148:149], v[148:149], v[154:155]
	v_mov_b32_e32 v155, v146
	v_mov_b32_e32 v154, v148
	v_mov_b32_e32 v146, v149
	v_pk_add_f32 v[146:147], v[154:155], v[146:147]
	ds_bpermute_b32 v149, v217, v147
	ds_bpermute_b32 v148, v217, v146
	ds_bpermute_b32 v165, v217, v163
	ds_bpermute_b32 v164, v217, v162
	v_pk_fma_f32 v[210:211], v[210:211], s[38:39], v[178:179] op_sel_hi:[1,0,0]
	s_waitcnt lgkmcnt(2)
	v_pk_add_f32 v[154:155], v[146:147], v[148:149]
	v_mov_b32_e32 v146, v151
	v_mov_b32_e32 v147, v152
	v_mov_b32_e32 v151, v153
	v_mov_b32_e32 v148, v159
	v_mov_b32_e32 v149, v160
	v_mov_b32_e32 v159, v161
	v_pk_add_f32 v[146:147], v[146:147], v[150:151]
	v_pk_add_f32 v[148:149], v[148:149], v[158:159]
	v_mov_b32_e32 v151, v146
	v_mov_b32_e32 v150, v148
	v_mov_b32_e32 v146, v149
	v_pk_add_f32 v[146:147], v[150:151], v[146:147]
	ds_bpermute_b32 v149, v217, v147
	ds_bpermute_b32 v148, v217, v146
	v_mul_f32_e32 v212, 0x4b800000, v211
	v_cmp_gt_f32_e32 vcc, s20, v211
	s_waitcnt lgkmcnt(2)
	v_pk_add_f32 v[162:163], v[162:163], v[164:165]
	ds_bpermute_b32 v165, v0, v163
	v_cndmask_b32_e32 v211, v211, v212, vcc
	v_rsq_f32_e32 v211, v211
	s_waitcnt lgkmcnt(1)
	v_pk_add_f32 v[146:147], v[146:147], v[148:149]
	ds_bpermute_b32 v164, v0, v162
	ds_bpermute_b32 v157, v0, v155
	ds_bpermute_b32 v156, v0, v154
	ds_bpermute_b32 v149, v0, v147
	ds_bpermute_b32 v148, v0, v146
	v_mul_f32_e32 v212, 0x45800000, v211
	v_cndmask_b32_e32 v212, v211, v212, vcc
	v_cmp_gt_f32_e64 s[44:45], s20, v210
	v_pk_fma_f32 v[144:145], v[144:145], v[212:213], v[80:81] op_sel_hi:[1,0,1]
	v_pk_fma_f32 v[150:151], v[142:143], v[212:213], v[78:79] op_sel_hi:[1,0,1]
	v_pk_fma_f32 v[142:143], v[140:141], v[212:213], v[76:77] op_sel_hi:[1,0,1]
	v_pk_fma_f32 v[152:153], v[138:139], v[212:213], v[74:75] op_sel_hi:[1,0,1]
	s_cbranch_scc1 .LBB0_792
	v_mul_f32_e32 v0, 0x3d372713, v150
	v_mul_f32_e32 v0, v150, v0
	v_mul_f32_e32 v138, 0x3d372713, v152
	v_fma_f32 v0, v150, v0, v150
	v_mul_f32_e32 v138, v152, v138
	v_fma_f32 v138, v152, v138, v152
	v_mul_f32_e32 v0, 0xbfcc422a, v0
	v_mul_f32_e32 v0, 0x3fb8aa3b, v0
	v_mul_f32_e32 v138, 0xbfcc422a, v138
	v_exp_f32_e32 v0, v0
	v_mul_f32_e32 v138, 0x3fb8aa3b, v138
	v_exp_f32_e32 v139, v138
	v_mov_b32_e32 v141, v153
	v_add_f32_e32 v0, 1.0, v0
	v_rcp_f32_e32 v138, v0
	v_add_f32_e32 v0, 1.0, v139
	v_rcp_f32_e32 v140, v0
	v_mul_f32_e32 v0, 0x3d372713, v151
	v_mul_f32_e32 v0, v151, v0
	v_mov_b32_e32 v139, v151
	v_fmac_f32_e32 v139, v139, v0
	v_mul_f32_e32 v139, 0xbfcc422a, v139
	v_mul_f32_e32 v139, 0x3fb8aa3b, v139
	v_exp_f32_e32 v139, v139
	v_mul_f32_e32 v0, 0x3d372713, v153
	v_mul_f32_e32 v0, v153, v0
	v_fmac_f32_e32 v141, v141, v0
	v_add_f32_e32 v0, 1.0, v139
	v_rcp_f32_e32 v139, v0
	v_mul_f32_e32 v0, 0xbfcc422a, v141
	v_mul_f32_e32 v141, 0x3d372713, v144
	v_mul_f32_e32 v141, v144, v141
	v_mul_f32_e32 v158, 0x3d372713, v142
	v_fma_f32 v141, v144, v141, v144
	v_mul_f32_e32 v158, v142, v158
	v_fma_f32 v158, v142, v158, v142
	v_mul_f32_e32 v141, 0xbfcc422a, v141
	v_mul_f32_e32 v141, 0x3fb8aa3b, v141
	v_mul_f32_e32 v158, 0xbfcc422a, v158
	v_exp_f32_e32 v141, v141
	v_mul_f32_e32 v158, 0x3fb8aa3b, v158
	v_exp_f32_e32 v159, v158
	v_mul_f32_e32 v160, 0x3d372713, v143
	v_add_f32_e32 v141, 1.0, v141
	v_rcp_f32_e32 v158, v141
	v_add_f32_e32 v141, 1.0, v159
	v_mul_f32_e32 v159, 0x3d372713, v145
	v_mul_f32_e32 v159, v145, v159
	v_fma_f32 v159, v145, v159, v145
	v_mul_f32_e32 v160, v143, v160
	v_fma_f32 v160, v143, v160, v143
	v_mul_f32_e32 v159, 0xbfcc422a, v159
	v_mul_f32_e32 v159, 0x3fb8aa3b, v159
	v_mul_f32_e32 v160, 0xbfcc422a, v160
	v_mul_f32_e32 v0, 0x3fb8aa3b, v0
	v_exp_f32_e32 v159, v159
	v_mul_f32_e32 v160, 0x3fb8aa3b, v160
	v_exp_f32_e32 v0, v0
	v_exp_f32_e32 v161, v160
	v_rcp_f32_e32 v160, v141
	v_add_f32_e32 v141, 1.0, v159
	v_add_f32_e32 v0, 1.0, v0
	v_rcp_f32_e32 v159, v141
	v_add_f32_e32 v141, 1.0, v161
	v_rcp_f32_e32 v161, v141
	v_rcp_f32_e32 v141, v0
	v_pk_mul_f32 v[144:145], v[144:145], v[158:159]
	v_pk_mul_f32 v[150:151], v[150:151], v[138:139]
	v_pk_mul_f32 v[142:143], v[142:143], v[160:161]
	v_pk_mul_f32 v[152:153], v[152:153], v[140:141]

.LBB0_806:
	s_waitcnt lgkmcnt(2)
	v_pk_add_f32 v[82:83], v[154:155], v[156:157]
	v_cvt_pk_bf16_f32 v92, v92, v93
	v_cvt_pk_bf16_f32 v93, v88, v89
	v_cvt_pk_bf16_f32 v94, v94, v95
	v_cvt_pk_bf16_f32 v95, v86, v87
	global_store_dwordx4 v[90:91], v[92:95], off offset:256
	s_cmp_lg_u32 s100, 0
	s_cbranch_scc0 .Lh2_f
	s_andn2_b64 vcc, exec, s[40:41]
	s_mov_b64 s[0:1], -1
	s_branch .Lh2_e
.Lh2_f:
	v_pk_fma_f32 v[82:83], v[82:83], s[38:39], v[178:179] op_sel_hi:[1,0,0]
	s_nop 0
	v_mul_f32_e32 v0, 0x4b800000, v83
	v_cmp_gt_f32_e32 vcc, s20, v83
	v_cmp_gt_f32_e64 s[44:45], s20, v82
	s_nop 0
	v_cndmask_b32_e32 v0, v83, v0, vcc
	v_rsq_f32_e32 v0, v0
	s_nop 0
	v_mul_f32_e32 v83, 0x45800000, v0
	v_cndmask_b32_e32 v84, v0, v83, vcc
	v_pk_fma_f32 v[72:73], v[72:73], v[84:85], v[80:81] op_sel_hi:[1,0,1]
	v_pk_fma_f32 v[70:71], v[70:71], v[84:85], v[78:79] op_sel_hi:[1,0,1]
	v_pk_fma_f32 v[64:65], v[64:65], v[84:85], v[76:77] op_sel_hi:[1,0,1]
	s_and_b64 vcc, exec, s[42:43]
	v_pk_fma_f32 v[86:87], v[62:63], v[84:85], v[74:75] op_sel_hi:[1,0,1]
	s_cbranch_vccnz .LBB0_808
	v_mul_f32_e32 v0, 0x3d372713, v70
	v_mul_f32_e32 v0, v70, v0
	v_mul_f32_e32 v62, 0x3d372713, v86
	v_fma_f32 v0, v70, v0, v70
	v_mul_f32_e32 v62, v86, v62
	v_fma_f32 v62, v86, v62, v86
	v_mul_f32_e32 v0, 0xbfcc422a, v0
	v_mul_f32_e32 v0, 0x3fb8aa3b, v0
	v_mul_f32_e32 v62, 0xbfcc422a, v62
	v_exp_f32_e32 v0, v0
	v_mul_f32_e32 v62, 0x3fb8aa3b, v62
	v_exp_f32_e32 v63, v62
	v_mov_b32_e32 v83, v87
	v_add_f32_e32 v0, 1.0, v0
	v_rcp_f32_e32 v62, v0
	v_add_f32_e32 v0, 1.0, v63
	v_rcp_f32_e32 v88, v0
	v_mul_f32_e32 v0, 0x3d372713, v71
	v_mul_f32_e32 v0, v71, v0
	v_mov_b32_e32 v63, v71
	v_fmac_f32_e32 v63, v63, v0
	v_mul_f32_e32 v63, 0xbfcc422a, v63
	v_mul_f32_e32 v63, 0x3fb8aa3b, v63
	v_exp_f32_e32 v63, v63
	v_mul_f32_e32 v0, 0x3d372713, v87
	v_mul_f32_e32 v0, v87, v0
	v_fmac_f32_e32 v83, v83, v0
	v_add_f32_e32 v0, 1.0, v63
	v_rcp_f32_e32 v63, v0
	v_mul_f32_e32 v0, 0xbfcc422a, v83
	v_mul_f32_e32 v83, 0x3d372713, v72
	v_mul_f32_e32 v83, v72, v83
	v_mul_f32_e32 v85, 0x3d372713, v64
	v_fma_f32 v83, v72, v83, v72
	v_mul_f32_e32 v85, v64, v85
	v_fma_f32 v85, v64, v85, v64
	v_mul_f32_e32 v83, 0xbfcc422a, v83
	v_mul_f32_e32 v83, 0x3fb8aa3b, v83
	v_mul_f32_e32 v85, 0xbfcc422a, v85
	v_exp_f32_e32 v83, v83
	v_mul_f32_e32 v85, 0x3fb8aa3b, v85
	v_exp_f32_e32 v85, v85
	v_mul_f32_e32 v89, 0x3d372713, v65
	v_add_f32_e32 v83, 1.0, v83
	v_rcp_f32_e32 v90, v83
	v_add_f32_e32 v83, 1.0, v85
	v_mul_f32_e32 v85, 0x3d372713, v73
	v_mul_f32_e32 v85, v73, v85
	v_fma_f32 v85, v73, v85, v73
	v_mul_f32_e32 v89, v65, v89
	v_fma_f32 v89, v65, v89, v65
	v_mul_f32_e32 v85, 0xbfcc422a, v85
	v_mul_f32_e32 v85, 0x3fb8aa3b, v85
	v_mul_f32_e32 v89, 0xbfcc422a, v89
	v_mul_f32_e32 v0, 0x3fb8aa3b, v0
	v_exp_f32_e32 v85, v85
	v_mul_f32_e32 v89, 0x3fb8aa3b, v89
	v_exp_f32_e32 v0, v0
	v_exp_f32_e32 v89, v89
	v_rcp_f32_e32 v92, v83
	v_add_f32_e32 v83, 1.0, v85
	v_add_f32_e32 v0, 1.0, v0
	v_rcp_f32_e32 v91, v83
	v_add_f32_e32 v83, 1.0, v89
	v_rcp_f32_e32 v93, v83
	v_rcp_f32_e32 v89, v0
	v_pk_mul_f32 v[72:73], v[72:73], v[90:91]
	v_pk_mul_f32 v[70:71], v[70:71], v[62:63]
	v_pk_mul_f32 v[64:65], v[64:65], v[92:93]
	v_pk_mul_f32 v[86:87], v[86:87], v[88:89]

.Lh2_e:
	s_cbranch_vccnz .LBB0_781
	s_andn2_b64 vcc, exec, s[48:49]
	s_cbranch_vccnz .LBB0_780
	s_barrier
	s_branch .LBB0_780
